# GEMM2 and GEMM4 epilogues: all residual (x_prompt / X1B) lines of the serialised load ladder touched together up front; plus st_ffn prefetch, no-setprio K-loops, P0 split, nt loads
# baseline (speedup 1.0000x reference)
; __device__ __forceinline__ unsigned cvt_pk_bf16(float lo, float hi) { unsigned r; asm volatile("v_cvt_pk_bf16_f32 %0, %1, %2" : "=v"(r) : "v"(lo), "v"(hi)); return r; }
;     __device__ __forceinline__ void operator()(const f32x4 (&acc)[2][2][4][2], const Unit& u, int wr, int wc, int fr, int fq) const {
;         const int row0 = u.pm * BM + wr * 64 + fr; const int col0 = u.pn * BM + wc * 32 + 8 * fq;
; #pragma unroll
;         for (int ai = 0; ai < 2; ++ai)
; #pragma unroll
;             for (int m = 0; m < 4; ++m) { const int row = row0 + ai * HALF + m * 16; const size_t off = (size_t)row * ldc + col0; float ss = 0.f;
; #pragma unroll
;                 for (int bj = 0; bj < 2; ++bj) { const f32x4 v0 = *(const f32x4*)(base + off + bj * HALF) + acc[ai][bj][m][0], v1 = *(const f32x4*)(base + off + bj * HALF + 4) + acc[ai][bj][m][1];
;                     ss += (v0[0] * v0[0] + v0[1] * v0[1]) + (v0[2] * v0[2] + v0[3] * v0[3]) + (v1[0] * v1[0] + v1[1] * v1[1]) + (v1[2] * v1[2] + v1[3] * v1[3]);
;                     u32x4 w; w.x = cvt_pk_bf16(v0[0], v0[1]); w.y = cvt_pk_bf16(v0[2], v0[3]); w.z = cvt_pk_bf16(v1[0], v1[1]); w.w = cvt_pk_bf16(v1[2], v1[3]);
;                     *(u32x4*)(O + off + bj * HALF) = w; }
;                 ss += __shfl_xor(ss, 16); ss += __shfl_xor(ss, 32);
;                 if (fq == 0) atomicAdd(ssq + row, ss);
.LBB0_516:
	s_cmp_lg_u32 s9, 1
	s_cselect_b64 s[42:43], -1, 0
	s_lshl_b32 s12, s10, 8
	v_add_u32_e32 v4, s12, v160
	s_mov_b64 s[10:11], -1
	s_and_b64 vcc, exec, s[42:43]
	v_ashrrev_i32_e32 v5, 31, v4
	s_cbranch_vccz .LBB0_535
	v_lshl_or_b32 v152, s8, 8, v169
	v_ashrrev_i32_e32 v153, 31, v152
	v_lshlrev_b64 v[154:155], 12, v[4:5]
	v_lshl_add_u64 v[154:155], v[154:155], 0, v[152:153]
	v_lshl_add_u64 v[182:183], v[154:155], 2, s[18:19]
	global_load_dword v252, v[182:183], off offset:512
	s_mov_b64 s[98:99], 0x40000
	v_lshl_add_u64 v[250:251], v[182:183], 0, s[98:99]
	global_load_dword v252, v[250:251], off
	global_load_dword v252, v[250:251], off offset:512
	s_mov_b64 s[98:99], 0x80000
	v_lshl_add_u64 v[250:251], v[182:183], 0, s[98:99]
	global_load_dword v252, v[250:251], off
	global_load_dword v252, v[250:251], off offset:512
	s_mov_b64 s[98:99], 0xc0000
	v_lshl_add_u64 v[250:251], v[182:183], 0, s[98:99]
	global_load_dword v252, v[250:251], off
	global_load_dword v252, v[250:251], off offset:512
	s_mov_b64 s[98:99], 0x200000
	v_lshl_add_u64 v[250:251], v[182:183], 0, s[98:99]
	global_load_dword v252, v[250:251], off
	global_load_dword v252, v[250:251], off offset:512
	s_mov_b64 s[98:99], 0x240000
	v_lshl_add_u64 v[250:251], v[182:183], 0, s[98:99]
	global_load_dword v252, v[250:251], off
	global_load_dword v252, v[250:251], off offset:512
	s_mov_b64 s[98:99], 0x280000
	v_lshl_add_u64 v[250:251], v[182:183], 0, s[98:99]
	global_load_dword v252, v[250:251], off
	global_load_dword v252, v[250:251], off offset:512
	s_mov_b64 s[98:99], 0x2c0000
	v_lshl_add_u64 v[250:251], v[182:183], 0, s[98:99]
	global_load_dword v252, v[250:251], off
	global_load_dword v252, v[250:251], off offset:512
	global_load_dwordx4 v[174:177], v[182:183], off
	global_load_dwordx4 v[178:181], v[182:183], off offset:16
	v_lshl_add_u64 v[184:185], v[154:155], 1, s[22:23]
	v_xor_b32_e32 v3, 16, v173
	s_waitcnt vmcnt(0)
	v_pk_add_f32 v[154:155], v[132:133], v[176:177]
	v_pk_add_f32 v[186:187], v[130:131], v[174:175]
	v_pk_add_f32 v[190:191], v[128:129], v[180:181]
	v_pk_add_f32 v[192:193], v[126:127], v[178:179]
	v_cvt_pk_bf16_f32 v174, v186, v187
	v_cvt_pk_bf16_f32 v175, v154, v155
	v_mul_f32_e32 v155, v155, v155
	v_cvt_pk_bf16_f32 v176, v192, v193
	v_cvt_pk_bf16_f32 v177, v190, v191
	global_store_dwordx4 v[184:185], v[174:177], off
	global_load_dwordx4 v[174:177], v[182:183], off offset:512
	s_nop 0
	global_load_dwordx4 v[178:181], v[182:183], off offset:528
	v_and_b32_e32 v182, 64, v173
	v_add_u32_e32 v188, 64, v182
	v_mul_f32_e32 v182, v187, v187
	v_mul_f32_e32 v183, v193, v193
	v_fmac_f32_e32 v182, v186, v186
	v_fmac_f32_e32 v155, v154, v154
	v_mul_f32_e32 v187, v191, v191
	v_fmac_f32_e32 v183, v192, v192
	v_add_f32_e32 v154, v182, v155
	v_fmac_f32_e32 v187, v190, v190
	v_add_f32_e32 v154, v154, v183
	v_add_f32_e32 v186, v187, v154
	v_cmp_lt_i32_e32 vcc, v3, v188
	s_waitcnt vmcnt(1)
	v_pk_add_f32 v[182:183], v[100:101], v[176:177]
	v_pk_add_f32 v[154:155], v[98:99], v[174:175]
	s_waitcnt vmcnt(0)
	v_pk_add_f32 v[178:179], v[94:95], v[178:179]
	v_mul_f32_e32 v174, v155, v155
	v_mul_f32_e32 v175, v183, v183
	v_pk_add_f32 v[180:181], v[96:97], v[180:181]
	v_mul_f32_e32 v176, v179, v179
	v_fmac_f32_e32 v174, v154, v154
	v_fmac_f32_e32 v175, v182, v182
	v_mul_f32_e32 v177, v181, v181
	v_fmac_f32_e32 v176, v178, v178
	v_add_f32_e32 v174, v174, v175
	v_fmac_f32_e32 v177, v180, v180
	v_add_f32_e32 v174, v174, v176
	v_cndmask_b32_e32 v3, v173, v3, vcc
	v_add_f32_e32 v174, v177, v174
	v_lshlrev_b32_e32 v3, 2, v3
	v_add_f32_e32 v174, v186, v174
	ds_bpermute_b32 v175, v3, v174
	v_xor_b32_e32 v176, 32, v173
	v_cmp_lt_i32_e32 vcc, v176, v188
	s_nop 1
	v_cndmask_b32_e32 v177, v173, v176, vcc
	v_cvt_pk_bf16_f32 v176, v154, v155
	s_waitcnt lgkmcnt(0)
	v_add_f32_e32 v154, v174, v175
	v_lshlrev_b32_e32 v174, 2, v177
	ds_bpermute_b32 v155, v174, v154
	v_cvt_pk_bf16_f32 v177, v182, v183
	v_cvt_pk_bf16_f32 v178, v178, v179
	v_cvt_pk_bf16_f32 v179, v180, v181
	global_store_dwordx4 v[184:185], v[176:179], off offset:256
	s_and_saveexec_b64 s[8:9], s[4:5]
	s_cbranch_execz .LBB0_519
	v_lshl_add_u64 v[176:177], v[4:5], 2, s[24:25]
	s_waitcnt lgkmcnt(0)
	v_add_f32_e32 v154, v154, v155
	global_atomic_add_f32 v[176:177], v154, off

;     __device__ __forceinline__ void operator()(const f32x4 (&acc)[2][2][4][2], const Unit& u, int wr, int wc, int fr, int fq) const {
;         const int row0 = u.pm * BM + wr * 64 + fr; const int col0 = u.pn * BM + wc * 32 + 8 * fq;
; #pragma unroll
;         for (int ai = 0; ai < 2; ++ai)
; #pragma unroll
;             for (int m = 0; m < 4; ++m) { const size_t off = (size_t)(row0 + ai * HALF + m * 16) * ldc + col0;
; #pragma unroll
;                 for (int bj = 0; bj < 2; ++bj) { const u32x4 w = *(const u32x4*)(X + off + bj * HALF);
;                     f32x4 b0, b1; b0[0] = __uint_as_float(w.x << 16); b0[1] = __uint_as_float(w.x & 0xffff0000u); b0[2] = __uint_as_float(w.y << 16); b0[3] = __uint_as_float(w.y & 0xffff0000u);
;                     b1[0] = __uint_as_float(w.z << 16); b1[1] = __uint_as_float(w.z & 0xffff0000u); b1[2] = __uint_as_float(w.w << 16); b1[3] = __uint_as_float(w.w & 0xffff0000u);
;                     *(f32x4*)(out + off + bj * HALF) = b0 + acc[ai][bj][m][0]; *(f32x4*)(out + off + bj * HALF + 4) = b1 + acc[ai][bj][m][1]; }
.LBB0_1072:
	v_lshl_add_u32 v146, s63, 8, v158
	v_lshl_or_b32 v144, s64, 8, v160
	v_ashrrev_i32_e32 v147, 31, v146
	v_ashrrev_i32_e32 v145, 31, v144
	v_lshlrev_b64 v[142:143], 12, v[146:147]
	v_lshl_add_u64 v[142:143], v[142:143], 0, v[144:145]
	v_lshl_add_u64 v[168:169], v[142:143], 1, s[14:15]
	global_load_dword v252, v[168:169], off offset:256
	s_mov_b64 s[98:99], 0x20000
	v_lshl_add_u64 v[250:251], v[168:169], 0, s[98:99]
	global_load_dword v252, v[250:251], off
	global_load_dword v252, v[250:251], off offset:256
	s_mov_b64 s[98:99], 0x40000
	v_lshl_add_u64 v[250:251], v[168:169], 0, s[98:99]
	global_load_dword v252, v[250:251], off
	global_load_dword v252, v[250:251], off offset:256
	s_mov_b64 s[98:99], 0x60000
	v_lshl_add_u64 v[250:251], v[168:169], 0, s[98:99]
	global_load_dword v252, v[250:251], off
	global_load_dword v252, v[250:251], off offset:256
	s_mov_b64 s[98:99], 0x100000
	v_lshl_add_u64 v[250:251], v[168:169], 0, s[98:99]
	global_load_dword v252, v[250:251], off
	global_load_dword v252, v[250:251], off offset:256
	s_mov_b64 s[98:99], 0x120000
	v_lshl_add_u64 v[250:251], v[168:169], 0, s[98:99]
	global_load_dword v252, v[250:251], off
	global_load_dword v252, v[250:251], off offset:256
	s_mov_b64 s[98:99], 0x140000
	v_lshl_add_u64 v[250:251], v[168:169], 0, s[98:99]
	global_load_dword v252, v[250:251], off
	global_load_dword v252, v[250:251], off offset:256
	s_mov_b64 s[98:99], 0x160000
	v_lshl_add_u64 v[250:251], v[168:169], 0, s[98:99]
	global_load_dword v252, v[250:251], off
	global_load_dword v252, v[250:251], off offset:256
	global_load_dwordx4 v[164:167], v[168:169], off
	v_lshl_add_u64 v[170:171], v[142:143], 2, s[10:11]
	s_and_b64 vcc, exec, s[6:7]
	s_mov_b64 s[6:7], -1
	s_waitcnt vmcnt(0)
	v_lshlrev_b32_e32 v172, 16, v164
	v_and_b32_e32 v173, 0xffff0000, v164
	v_lshlrev_b32_e32 v164, 16, v165
	v_and_b32_e32 v165, 0xffff0000, v165
	v_lshlrev_b32_e32 v174, 16, v166
	v_and_b32_e32 v175, 0xffff0000, v166
	v_lshlrev_b32_e32 v166, 16, v167
	v_and_b32_e32 v167, 0xffff0000, v167
	v_pk_add_f32 v[128:129], v[128:129], v[164:165]
	v_pk_add_f32 v[126:127], v[126:127], v[172:173]
	v_pk_add_f32 v[124:125], v[124:125], v[166:167]
	v_pk_add_f32 v[122:123], v[122:123], v[174:175]
	global_store_dwordx4 v[170:171], v[126:129], off
	global_store_dwordx4 v[170:171], v[122:125], off offset:16
	global_load_dwordx4 v[122:125], v[168:169], off offset:256
	v_or_b32_e32 v126, 16, v146
	v_ashrrev_i32_e32 v127, 31, v126
	v_lshlrev_b64 v[126:127], 12, v[126:127]
	v_lshl_add_u64 v[126:127], v[126:127], 0, v[144:145]
	v_lshl_add_u64 v[128:129], v[126:127], 1, s[14:15]
	s_waitcnt vmcnt(0)
	v_lshlrev_b32_e32 v164, 16, v122
	v_and_b32_e32 v165, 0xffff0000, v122
	v_lshlrev_b32_e32 v122, 16, v123
	v_and_b32_e32 v123, 0xffff0000, v123
	v_lshlrev_b32_e32 v166, 16, v124
	v_and_b32_e32 v167, 0xffff0000, v124
	v_lshlrev_b32_e32 v124, 16, v125
	v_and_b32_e32 v125, 0xffff0000, v125
	v_pk_add_f32 v[120:121], v[120:121], v[122:123]
	v_pk_add_f32 v[118:119], v[118:119], v[164:165]
	v_pk_add_f32 v[116:117], v[116:117], v[124:125]
	v_pk_add_f32 v[114:115], v[114:115], v[166:167]
	global_store_dwordx4 v[170:171], v[118:121], off offset:512
	global_store_dwordx4 v[170:171], v[114:117], off offset:528
	global_load_dwordx4 v[114:117], v[128:129], off
	v_lshl_add_u64 v[118:119], v[126:127], 2, s[10:11]
	s_waitcnt vmcnt(0)
	v_lshlrev_b32_e32 v120, 16, v114
	v_and_b32_e32 v121, 0xffff0000, v114
	v_lshlrev_b32_e32 v114, 16, v115
	v_and_b32_e32 v115, 0xffff0000, v115
	v_lshlrev_b32_e32 v122, 16, v116
	v_and_b32_e32 v123, 0xffff0000, v116
	v_lshlrev_b32_e32 v116, 16, v117
	v_and_b32_e32 v117, 0xffff0000, v117
	v_pk_add_f32 v[112:113], v[112:113], v[114:115]
	v_pk_add_f32 v[110:111], v[110:111], v[120:121]
	v_pk_add_f32 v[108:109], v[108:109], v[116:117]
	v_pk_add_f32 v[106:107], v[106:107], v[122:123]
	global_store_dwordx4 v[118:119], v[110:113], off
	global_store_dwordx4 v[118:119], v[106:109], off offset:16
	global_load_dwordx4 v[106:109], v[128:129], off offset:256
	v_or_b32_e32 v110, 32, v146
	v_ashrrev_i32_e32 v111, 31, v110
	v_lshlrev_b64 v[110:111], 12, v[110:111]
	v_lshl_add_u64 v[110:111], v[110:111], 0, v[144:145]
	v_lshl_add_u64 v[112:113], v[110:111], 1, s[14:15]
	s_waitcnt vmcnt(0)
	v_lshlrev_b32_e32 v114, 16, v106
	v_and_b32_e32 v115, 0xffff0000, v106
	v_lshlrev_b32_e32 v106, 16, v107
	v_and_b32_e32 v107, 0xffff0000, v107
	v_lshlrev_b32_e32 v116, 16, v108
	v_and_b32_e32 v117, 0xffff0000, v108
	v_lshlrev_b32_e32 v108, 16, v109
	v_and_b32_e32 v109, 0xffff0000, v109
	v_pk_add_f32 v[104:105], v[104:105], v[106:107]
	v_pk_add_f32 v[102:103], v[102:103], v[114:115]
	v_pk_add_f32 v[100:101], v[100:101], v[108:109]
	v_pk_add_f32 v[98:99], v[98:99], v[116:117]
	global_store_dwordx4 v[118:119], v[102:105], off offset:512
	global_store_dwordx4 v[118:119], v[98:101], off offset:528
	global_load_dwordx4 v[98:101], v[112:113], off
	v_lshl_add_u64 v[102:103], v[110:111], 2, s[10:11]
	s_waitcnt vmcnt(0)
	v_lshlrev_b32_e32 v104, 16, v98
	v_and_b32_e32 v105, 0xffff0000, v98
	v_lshlrev_b32_e32 v98, 16, v99
	v_and_b32_e32 v99, 0xffff0000, v99
	v_lshlrev_b32_e32 v106, 16, v100
	v_and_b32_e32 v107, 0xffff0000, v100
	v_lshlrev_b32_e32 v100, 16, v101
	v_and_b32_e32 v101, 0xffff0000, v101
	v_pk_add_f32 v[96:97], v[96:97], v[98:99]
	v_pk_add_f32 v[94:95], v[94:95], v[104:105]
	v_pk_add_f32 v[92:93], v[92:93], v[100:101]
	v_pk_add_f32 v[90:91], v[90:91], v[106:107]
	global_store_dwordx4 v[102:103], v[94:97], off
	global_store_dwordx4 v[102:103], v[90:93], off offset:16
	global_load_dwordx4 v[90:93], v[112:113], off offset:256
	v_or_b32_e32 v94, 48, v146
	v_ashrrev_i32_e32 v95, 31, v94
	v_lshlrev_b64 v[94:95], 12, v[94:95]
	v_lshl_add_u64 v[94:95], v[94:95], 0, v[144:145]
	v_lshl_add_u64 v[96:97], v[94:95], 1, s[14:15]
	s_waitcnt vmcnt(0)
;     __device__ __forceinline__ void operator()(const f32x4 (&acc)[2][2][4][2], const Unit& u, int wr, int wc, int fr, int fq) const {
;     ...
;                 for (int bj = 0; bj < 2; ++bj) { const u32x4 w = *(const u32x4*)(X + off + bj * HALF);
;                     f32x4 b0, b1; b0[0] = __uint_as_float(w.x << 16); b0[1] = __uint_as_float(w.x & 0xffff0000u); b0[2] = __uint_as_float(w.y << 16); b0[3] = __uint_as_float(w.y & 0xffff0000u);
;                     b1[0] = __uint_as_float(w.z << 16); b1[1] = __uint_as_float(w.z & 0xffff0000u); b1[2] = __uint_as_float(w.w << 16); b1[3] = __uint_as_float(w.w & 0xffff0000u);
;                     *(f32x4*)(out + off + bj * HALF) = b0 + acc[ai][bj][m][0]; *(f32x4*)(out + off + bj * HALF + 4) = b1 + acc[ai][bj][m][1]; }
	v_lshlrev_b32_e32 v98, 16, v90
	v_and_b32_e32 v99, 0xffff0000, v90
	v_lshlrev_b32_e32 v90, 16, v91
	v_and_b32_e32 v91, 0xffff0000, v91
	v_lshlrev_b32_e32 v100, 16, v92
	v_and_b32_e32 v101, 0xffff0000, v92
	v_lshlrev_b32_e32 v92, 16, v93
	v_and_b32_e32 v93, 0xffff0000, v93
	v_pk_add_f32 v[88:89], v[88:89], v[90:91]
	v_pk_add_f32 v[86:87], v[86:87], v[98:99]
	v_pk_add_f32 v[84:85], v[84:85], v[92:93]
	v_pk_add_f32 v[82:83], v[82:83], v[100:101]
	global_store_dwordx4 v[102:103], v[86:89], off offset:512
	global_store_dwordx4 v[102:103], v[82:85], off offset:528
	global_load_dwordx4 v[82:85], v[96:97], off
	v_lshl_add_u64 v[86:87], v[94:95], 2, s[10:11]
	s_waitcnt vmcnt(0)
	v_lshlrev_b32_e32 v88, 16, v82
	v_and_b32_e32 v89, 0xffff0000, v82
	v_lshlrev_b32_e32 v82, 16, v83
	v_and_b32_e32 v83, 0xffff0000, v83
	v_lshlrev_b32_e32 v90, 16, v84
	v_and_b32_e32 v91, 0xffff0000, v84
	v_lshlrev_b32_e32 v84, 16, v85
	v_and_b32_e32 v85, 0xffff0000, v85
	v_pk_add_f32 v[80:81], v[80:81], v[82:83]
	v_pk_add_f32 v[78:79], v[78:79], v[88:89]
	v_pk_add_f32 v[76:77], v[76:77], v[84:85]
	v_pk_add_f32 v[74:75], v[74:75], v[90:91]
	global_store_dwordx4 v[86:87], v[78:81], off
	global_store_dwordx4 v[86:87], v[74:77], off offset:16
	global_load_dwordx4 v[74:77], v[96:97], off offset:256
	v_lshl_add_u64 v[78:79], v[142:143], 0, s[20:21]
	v_lshl_add_u64 v[80:81], v[78:79], 1, s[14:15]
	s_waitcnt vmcnt(0)
	v_lshlrev_b32_e32 v82, 16, v74
	v_and_b32_e32 v83, 0xffff0000, v74
	v_lshlrev_b32_e32 v74, 16, v75
	v_and_b32_e32 v75, 0xffff0000, v75
	v_lshlrev_b32_e32 v84, 16, v76
	v_and_b32_e32 v85, 0xffff0000, v76
	v_lshlrev_b32_e32 v76, 16, v77
	v_and_b32_e32 v77, 0xffff0000, v77
	v_pk_add_f32 v[72:73], v[72:73], v[74:75]
	v_pk_add_f32 v[70:71], v[70:71], v[82:83]
	v_pk_add_f32 v[68:69], v[68:69], v[76:77]
	v_pk_add_f32 v[66:67], v[66:67], v[84:85]
	global_store_dwordx4 v[86:87], v[70:73], off offset:512
	global_store_dwordx4 v[86:87], v[66:69], off offset:528
	global_load_dwordx4 v[66:69], v[80:81], off
	v_lshl_add_u64 v[70:71], v[78:79], 2, s[10:11]
	s_waitcnt vmcnt(0)
	v_lshlrev_b32_e32 v72, 16, v66
	v_and_b32_e32 v73, 0xffff0000, v66
	v_lshlrev_b32_e32 v66, 16, v67
	v_and_b32_e32 v67, 0xffff0000, v67
	v_lshlrev_b32_e32 v74, 16, v68
	v_and_b32_e32 v75, 0xffff0000, v68
	v_lshlrev_b32_e32 v68, 16, v69
	v_and_b32_e32 v69, 0xffff0000, v69
	v_pk_add_f32 v[64:65], v[64:65], v[66:67]
	v_pk_add_f32 v[62:63], v[62:63], v[72:73]
	v_pk_add_f32 v[60:61], v[60:61], v[68:69]
	v_pk_add_f32 v[58:59], v[58:59], v[74:75]
	global_store_dwordx4 v[70:71], v[62:65], off
	global_store_dwordx4 v[70:71], v[58:61], off offset:16
	global_load_dwordx4 v[58:61], v[80:81], off offset:256
	v_lshl_add_u64 v[62:63], v[142:143], 0, s[22:23]
	v_lshl_add_u64 v[64:65], v[62:63], 1, s[14:15]
	s_waitcnt vmcnt(0)
	v_lshlrev_b32_e32 v66, 16, v58
	v_and_b32_e32 v67, 0xffff0000, v58
	v_lshlrev_b32_e32 v58, 16, v59
	v_and_b32_e32 v59, 0xffff0000, v59
	v_lshlrev_b32_e32 v68, 16, v60
	v_and_b32_e32 v69, 0xffff0000, v60
	v_lshlrev_b32_e32 v60, 16, v61
	v_and_b32_e32 v61, 0xffff0000, v61
	v_pk_add_f32 v[56:57], v[56:57], v[58:59]
	v_pk_add_f32 v[54:55], v[54:55], v[66:67]
	v_pk_add_f32 v[52:53], v[52:53], v[60:61]
	v_pk_add_f32 v[50:51], v[50:51], v[68:69]
	global_store_dwordx4 v[70:71], v[54:57], off offset:512
	global_store_dwordx4 v[70:71], v[50:53], off offset:528
	global_load_dwordx4 v[50:53], v[64:65], off
	v_lshl_add_u64 v[54:55], v[62:63], 2, s[10:11]
	s_waitcnt vmcnt(0)
;     __device__ __forceinline__ void operator()(const f32x4 (&acc)[2][2][4][2], const Unit& u, int wr, int wc, int fr, int fq) const {
;     ...
;                 for (int bj = 0; bj < 2; ++bj) { const u32x4 w = *(const u32x4*)(X + off + bj * HALF);
;                     f32x4 b0, b1; b0[0] = __uint_as_float(w.x << 16); b0[1] = __uint_as_float(w.x & 0xffff0000u); b0[2] = __uint_as_float(w.y << 16); b0[3] = __uint_as_float(w.y & 0xffff0000u);
;                     b1[0] = __uint_as_float(w.z << 16); b1[1] = __uint_as_float(w.z & 0xffff0000u); b1[2] = __uint_as_float(w.w << 16); b1[3] = __uint_as_float(w.w & 0xffff0000u);
;                     *(f32x4*)(out + off + bj * HALF) = b0 + acc[ai][bj][m][0]; *(f32x4*)(out + off + bj * HALF + 4) = b1 + acc[ai][bj][m][1]; }
;                 if (m & 1) asm volatile("" ::: "memory"); }
	v_lshlrev_b32_e32 v56, 16, v50
	v_and_b32_e32 v57, 0xffff0000, v50
	v_lshlrev_b32_e32 v50, 16, v51
	v_and_b32_e32 v51, 0xffff0000, v51
	v_lshlrev_b32_e32 v58, 16, v52
	v_and_b32_e32 v59, 0xffff0000, v52
	v_lshlrev_b32_e32 v52, 16, v53
	v_and_b32_e32 v53, 0xffff0000, v53
	v_pk_add_f32 v[48:49], v[48:49], v[50:51]
	v_pk_add_f32 v[46:47], v[46:47], v[56:57]
	v_pk_add_f32 v[44:45], v[44:45], v[52:53]
	v_pk_add_f32 v[42:43], v[42:43], v[58:59]
	global_store_dwordx4 v[54:55], v[46:49], off
	global_store_dwordx4 v[54:55], v[42:45], off offset:16
	global_load_dwordx4 v[42:45], v[64:65], off offset:256
	v_lshl_add_u64 v[46:47], v[142:143], 0, s[24:25]
	v_lshl_add_u64 v[48:49], v[46:47], 1, s[14:15]
	s_waitcnt vmcnt(0)
	v_lshlrev_b32_e32 v50, 16, v42
	v_and_b32_e32 v51, 0xffff0000, v42
	v_lshlrev_b32_e32 v42, 16, v43
	v_and_b32_e32 v43, 0xffff0000, v43
	v_lshlrev_b32_e32 v52, 16, v44
	v_and_b32_e32 v53, 0xffff0000, v44
	v_lshlrev_b32_e32 v44, 16, v45
	v_and_b32_e32 v45, 0xffff0000, v45
	v_pk_add_f32 v[40:41], v[40:41], v[42:43]
	v_pk_add_f32 v[38:39], v[38:39], v[50:51]
	v_pk_add_f32 v[36:37], v[36:37], v[44:45]
	v_pk_add_f32 v[34:35], v[34:35], v[52:53]
	global_store_dwordx4 v[54:55], v[38:41], off offset:512
	global_store_dwordx4 v[54:55], v[34:37], off offset:528
	global_load_dwordx4 v[34:37], v[48:49], off
	v_lshl_add_u64 v[38:39], v[46:47], 2, s[10:11]
	s_waitcnt vmcnt(0)
	v_lshlrev_b32_e32 v40, 16, v34
	v_and_b32_e32 v41, 0xffff0000, v34
	v_lshlrev_b32_e32 v34, 16, v35
	v_and_b32_e32 v35, 0xffff0000, v35
	v_lshlrev_b32_e32 v42, 16, v36
	v_and_b32_e32 v43, 0xffff0000, v36
	v_lshlrev_b32_e32 v36, 16, v37
	v_and_b32_e32 v37, 0xffff0000, v37
	v_pk_add_f32 v[32:33], v[32:33], v[34:35]
	v_pk_add_f32 v[30:31], v[30:31], v[40:41]
	v_pk_add_f32 v[28:29], v[28:29], v[36:37]
	v_pk_add_f32 v[26:27], v[26:27], v[42:43]
	global_store_dwordx4 v[38:39], v[30:33], off
	global_store_dwordx4 v[38:39], v[26:29], off offset:16
	global_load_dwordx4 v[26:29], v[48:49], off offset:256
	v_lshl_add_u64 v[30:31], v[142:143], 0, s[26:27]
	v_lshl_add_u64 v[32:33], v[30:31], 1, s[14:15]
	s_waitcnt vmcnt(0)
	v_lshlrev_b32_e32 v34, 16, v26
	v_and_b32_e32 v35, 0xffff0000, v26
	v_lshlrev_b32_e32 v26, 16, v27
	v_and_b32_e32 v27, 0xffff0000, v27
	v_lshlrev_b32_e32 v36, 16, v28
	v_and_b32_e32 v37, 0xffff0000, v28
	v_lshlrev_b32_e32 v28, 16, v29
	v_and_b32_e32 v29, 0xffff0000, v29
	v_pk_add_f32 v[24:25], v[24:25], v[26:27]
	v_pk_add_f32 v[22:23], v[22:23], v[34:35]
	v_pk_add_f32 v[20:21], v[20:21], v[28:29]
	v_pk_add_f32 v[18:19], v[18:19], v[36:37]
	global_store_dwordx4 v[38:39], v[22:25], off offset:512
	global_store_dwordx4 v[38:39], v[18:21], off offset:528
	global_load_dwordx4 v[18:21], v[32:33], off
	v_lshl_add_u64 v[22:23], v[30:31], 2, s[10:11]
	s_waitcnt vmcnt(0)
	v_lshlrev_b32_e32 v24, 16, v18
	v_and_b32_e32 v25, 0xffff0000, v18
	v_lshlrev_b32_e32 v18, 16, v19
	v_and_b32_e32 v19, 0xffff0000, v19
	v_lshlrev_b32_e32 v26, 16, v20
	v_and_b32_e32 v27, 0xffff0000, v20
	v_lshlrev_b32_e32 v20, 16, v21
	v_and_b32_e32 v21, 0xffff0000, v21
	v_pk_add_f32 v[16:17], v[16:17], v[18:19]
	v_pk_add_f32 v[14:15], v[14:15], v[24:25]
	v_pk_add_f32 v[12:13], v[12:13], v[20:21]
	v_pk_add_f32 v[10:11], v[10:11], v[26:27]
	global_store_dwordx4 v[22:23], v[14:17], off
	global_store_dwordx4 v[22:23], v[10:13], off offset:16
	global_load_dwordx4 v[10:13], v[32:33], off offset:256
	s_waitcnt vmcnt(0)
	v_lshlrev_b32_e32 v14, 16, v10
	v_and_b32_e32 v15, 0xffff0000, v10
	v_lshlrev_b32_e32 v10, 16, v11
	v_and_b32_e32 v11, 0xffff0000, v11
	v_lshlrev_b32_e32 v16, 16, v12
	v_and_b32_e32 v17, 0xffff0000, v12
	v_lshlrev_b32_e32 v12, 16, v13
	v_and_b32_e32 v13, 0xffff0000, v13
	v_pk_add_f32 v[8:9], v[8:9], v[10:11]
	v_pk_add_f32 v[6:7], v[6:7], v[14:15]
	v_pk_add_f32 v[4:5], v[4:5], v[12:13]
	v_pk_add_f32 v[2:3], v[2:3], v[16:17]
	global_store_dwordx4 v[22:23], v[6:9], off offset:512
	global_store_dwordx4 v[22:23], v[2:5], off offset:528
	s_cbranch_vccnz .LBB0_1056
	s_andn2_b64 vcc, exec, s[12:13]
	s_cbranch_vccnz .LBB0_1055
	s_barrier
	s_branch .LBB0_1055
